# phase 10 epilogue: cache-warming prefetch of the branch-output lines for all 8 rounds at epilogue start
# speedup vs baseline: 1.0065x; 1.0065x over previous
.LBB0_898:
	ds_read_b128 v[136:139], v151
	ds_read_b128 v[168:171], v151 offset:1024
	ds_read_b128 v[172:175], v151 offset:2048
	ds_read_b128 v[176:179], v151 offset:3072
	s_add_u32 s28, s46, 0xfffc0080
	s_addc_u32 s29, s47, -1
	s_cmp_eq_u32 s74, 12
	s_cselect_b32 s51, s19, s29
	s_cselect_b32 s50, s21, s28
	s_cselect_b32 s49, s23, s73
	s_cselect_b32 s48, s27, s72
	v_lshl_add_u64 v[140:141], s[46:47], 0, v[128:129]
	s_add_i32 m0, s45, 0xc000
	ds_read_b128 v[194:197], v153
	ds_read_b128 v[198:201], v153 offset:1024
	ds_read_b128 v[202:205], v153 offset:2048
	ds_read_b128 v[206:209], v153 offset:3072
	ds_read_b128 v[210:213], v153 offset:4096
	ds_read_b128 v[214:217], v153 offset:5120
	ds_read_b128 v[218:221], v153 offset:6144
	ds_read_b128 v[222:225], v153 offset:7168
	global_load_lds_dwordx4 v[140:141], off
	v_lshl_add_u64 v[140:141], s[46:47], 0, v[130:131]
	s_add_i32 m0, s45, 0xe000
	s_nop 0
	global_load_lds_dwordx4 v[140:141], off
	s_waitcnt lgkmcnt(8)
	s_barrier
	s_waitcnt lgkmcnt(0)
	s_setprio 1
	s_waitcnt lgkmcnt(0)
	v_mfma_f32_16x16x32_bf16 v[124:127], v[136:139], v[194:197], v[124:127]
	v_mfma_f32_16x16x32_bf16 v[120:123], v[172:175], v[194:197], v[120:123]
	v_mfma_f32_16x16x32_bf16 v[108:111], v[136:139], v[202:205], v[108:111]
	v_mfma_f32_16x16x32_bf16 v[104:107], v[172:175], v[202:205], v[104:107]
	v_mfma_f32_16x16x32_bf16 v[92:95], v[136:139], v[210:213], v[92:95]
	v_mfma_f32_16x16x32_bf16 v[88:91], v[172:175], v[210:213], v[88:91]
	v_mfma_f32_16x16x32_bf16 v[76:79], v[136:139], v[218:221], v[76:79]
	v_mfma_f32_16x16x32_bf16 v[72:75], v[172:175], v[218:221], v[72:75]
	v_mfma_f32_16x16x32_bf16 v[124:127], v[168:171], v[198:201], v[124:127]
	v_mfma_f32_16x16x32_bf16 v[120:123], v[176:179], v[198:201], v[120:123]
	v_mfma_f32_16x16x32_bf16 v[108:111], v[168:171], v[206:209], v[108:111]
	v_mfma_f32_16x16x32_bf16 v[104:107], v[176:179], v[206:209], v[104:107]
	v_mfma_f32_16x16x32_bf16 v[92:95], v[168:171], v[214:217], v[92:95]
	v_mfma_f32_16x16x32_bf16 v[88:91], v[176:179], v[214:217], v[88:91]
	v_mfma_f32_16x16x32_bf16 v[76:79], v[168:171], v[222:225], v[76:79]
	v_mfma_f32_16x16x32_bf16 v[72:75], v[176:179], v[222:225], v[72:75]
	s_setprio 0
	s_barrier
	s_add_i32 s28, s70, s53
	v_lshl_add_u64 v[140:141], s[48:49], 0, v[158:159]
	s_mov_b32 m0, s28
	ds_read_b128 v[226:229], v155
	ds_read_b128 v[230:233], v155 offset:1024
	ds_read_b128 v[234:237], v155 offset:2048
	ds_read_b128 v[238:241], v155 offset:3072
	global_load_lds_dwordx4 v[140:141], off
	v_lshl_add_u64 v[242:243], s[48:49], 0, v[162:163]
	s_add_i32 m0, s28, 0x2000
	s_nop 0
	global_load_lds_dwordx4 v[242:243], off
	s_barrier
	s_waitcnt lgkmcnt(0)
	s_setprio 1
	s_waitcnt lgkmcnt(0)
	v_mfma_f32_16x16x32_bf16 v[116:119], v[226:229], v[194:197], v[116:119]
	v_mfma_f32_16x16x32_bf16 v[112:115], v[234:237], v[194:197], v[112:115]
	v_mfma_f32_16x16x32_bf16 v[100:103], v[226:229], v[202:205], v[100:103]
	v_mfma_f32_16x16x32_bf16 v[96:99], v[234:237], v[202:205], v[96:99]
	v_mfma_f32_16x16x32_bf16 v[84:87], v[226:229], v[210:213], v[84:87]
	v_mfma_f32_16x16x32_bf16 v[80:83], v[234:237], v[210:213], v[80:83]
	v_mfma_f32_16x16x32_bf16 v[68:71], v[226:229], v[218:221], v[68:71]
	v_mfma_f32_16x16x32_bf16 v[64:67], v[234:237], v[218:221], v[64:67]
	v_mfma_f32_16x16x32_bf16 v[116:119], v[230:233], v[198:201], v[116:119]
	v_mfma_f32_16x16x32_bf16 v[112:115], v[238:241], v[198:201], v[112:115]
	v_mfma_f32_16x16x32_bf16 v[100:103], v[230:233], v[206:209], v[100:103]
	v_mfma_f32_16x16x32_bf16 v[96:99], v[238:241], v[206:209], v[96:99]
	v_mfma_f32_16x16x32_bf16 v[84:87], v[230:233], v[214:217], v[84:87]
	v_mfma_f32_16x16x32_bf16 v[80:83], v[238:241], v[214:217], v[80:83]
	v_mfma_f32_16x16x32_bf16 v[68:71], v[230:233], v[222:225], v[68:71]
	v_mfma_f32_16x16x32_bf16 v[64:67], v[238:241], v[222:225], v[64:67]
	s_setprio 0
	s_mov_b32 m0, s45
	v_lshl_add_u64 v[244:245], s[50:51], 0, v[156:157]
	s_barrier
	ds_read_b128 v[194:197], v153 offset:16384
	ds_read_b128 v[198:201], v153 offset:17408
	ds_read_b128 v[202:205], v153 offset:18432
	ds_read_b128 v[206:209], v153 offset:19456
	ds_read_b128 v[210:213], v153 offset:20480
	ds_read_b128 v[214:217], v153 offset:21504
	ds_read_b128 v[218:221], v153 offset:22528
	ds_read_b128 v[222:225], v153 offset:23552
	global_load_lds_dwordx4 v[244:245], off
	v_lshl_add_u64 v[246:247], s[50:51], 0, v[160:161]
	s_mov_b32 m0, s4
	s_nop 0
	global_load_lds_dwordx4 v[246:247], off
	s_barrier
	s_waitcnt lgkmcnt(0)
	s_setprio 1
	s_waitcnt lgkmcnt(0)
	v_mfma_f32_16x16x32_bf16 v[60:63], v[136:139], v[194:197], v[60:63]
	v_mfma_f32_16x16x32_bf16 v[56:59], v[172:175], v[194:197], v[56:59]
	v_mfma_f32_16x16x32_bf16 v[44:47], v[136:139], v[202:205], v[44:47]
	v_mfma_f32_16x16x32_bf16 v[40:43], v[172:175], v[202:205], v[40:43]
	v_mfma_f32_16x16x32_bf16 v[28:31], v[136:139], v[210:213], v[28:31]
	v_mfma_f32_16x16x32_bf16 v[24:27], v[172:175], v[210:213], v[24:27]
	v_mfma_f32_16x16x32_bf16 v[12:15], v[136:139], v[218:221], v[12:15]
	v_mfma_f32_16x16x32_bf16 v[8:11], v[172:175], v[218:221], v[8:11]
	v_mfma_f32_16x16x32_bf16 v[60:63], v[168:171], v[198:201], v[60:63]
	v_mfma_f32_16x16x32_bf16 v[56:59], v[176:179], v[198:201], v[56:59]
	v_mfma_f32_16x16x32_bf16 v[44:47], v[168:171], v[206:209], v[44:47]
	v_mfma_f32_16x16x32_bf16 v[40:43], v[176:179], v[206:209], v[40:43]
	v_mfma_f32_16x16x32_bf16 v[28:31], v[168:171], v[214:217], v[28:31]
	v_mfma_f32_16x16x32_bf16 v[24:27], v[176:179], v[214:217], v[24:27]
	v_mfma_f32_16x16x32_bf16 v[12:15], v[168:171], v[222:225], v[12:15]
	v_mfma_f32_16x16x32_bf16 v[8:11], v[176:179], v[222:225], v[8:11]
	s_setprio 0
	s_barrier
	s_add_u32 s28, s48, 0x40000
	s_addc_u32 s29, s49, 0
	s_add_i32 s75, s71, s53
	v_lshl_add_u64 v[136:137], s[28:29], 0, v[158:159]
	s_mov_b32 m0, s75
	s_nop 0
	global_load_lds_dwordx4 v[136:137], off
	v_lshl_add_u64 v[136:137], s[28:29], 0, v[162:163]
	s_add_i32 m0, s75, 0x2000
	s_nop 0
	global_load_lds_dwordx4 v[136:137], off
	s_waitcnt vmcnt(6)
	s_barrier
	s_setprio 1
	v_mfma_f32_16x16x32_bf16 v[52:55], v[226:229], v[194:197], v[52:55]
	v_mfma_f32_16x16x32_bf16 v[48:51], v[234:237], v[194:197], v[48:51]
	v_mfma_f32_16x16x32_bf16 v[36:39], v[226:229], v[202:205], v[36:39]
	v_mfma_f32_16x16x32_bf16 v[32:35], v[234:237], v[202:205], v[32:35]
	v_mfma_f32_16x16x32_bf16 v[20:23], v[226:229], v[210:213], v[20:23]
	v_mfma_f32_16x16x32_bf16 v[16:19], v[234:237], v[210:213], v[16:19]
	v_mfma_f32_16x16x32_bf16 v[4:7], v[226:229], v[218:221], v[4:7]
	v_mfma_f32_16x16x32_bf16 v[0:3], v[234:237], v[218:221], v[0:3]
	v_mfma_f32_16x16x32_bf16 v[52:55], v[230:233], v[198:201], v[52:55]
	v_mfma_f32_16x16x32_bf16 v[48:51], v[238:241], v[198:201], v[48:51]
	v_mfma_f32_16x16x32_bf16 v[36:39], v[230:233], v[206:209], v[36:39]
	v_mfma_f32_16x16x32_bf16 v[32:35], v[238:241], v[206:209], v[32:35]
	v_mfma_f32_16x16x32_bf16 v[20:23], v[230:233], v[214:217], v[20:23]
	v_mfma_f32_16x16x32_bf16 v[16:19], v[238:241], v[214:217], v[16:19]
	v_mfma_f32_16x16x32_bf16 v[4:7], v[230:233], v[222:225], v[4:7]
	v_mfma_f32_16x16x32_bf16 v[0:3], v[238:241], v[222:225], v[0:3]
	s_setprio 0
	s_add_i32 s75, 0, 0x18000
	v_add_u32_e32 v164, s75, v143
	s_barrier
	ds_read_b128 v[136:139], v164
	ds_read_b128 v[168:171], v164 offset:1024
	ds_read_b128 v[172:175], v164 offset:2048
	ds_read_b128 v[176:179], v164 offset:3072
	s_add_u32 s28, s50, 0x40000
	s_addc_u32 s29, s51, 0
	s_mov_b32 m0, s5
	v_lshl_add_u64 v[226:227], s[28:29], 0, v[156:157]
	ds_read_b128 v[194:197], v153 offset:32768
	ds_read_b128 v[198:201], v153 offset:33792
	ds_read_b128 v[202:205], v153 offset:34816
	ds_read_b128 v[206:209], v153 offset:35840
	ds_read_b128 v[210:213], v153 offset:36864
	ds_read_b128 v[214:217], v153 offset:37888
	ds_read_b128 v[218:221], v153 offset:38912
	ds_read_b128 v[222:225], v153 offset:39936
	global_load_lds_dwordx4 v[226:227], off
	v_lshl_add_u64 v[226:227], s[28:29], 0, v[160:161]
	s_mov_b32 m0, s55
	s_nop 0
	global_load_lds_dwordx4 v[226:227], off
	s_waitcnt lgkmcnt(8)
	s_barrier
	s_waitcnt lgkmcnt(0)
	s_setprio 1
	s_waitcnt lgkmcnt(0)
	v_mfma_f32_16x16x32_bf16 v[124:127], v[136:139], v[194:197], v[124:127]
	v_mfma_f32_16x16x32_bf16 v[120:123], v[172:175], v[194:197], v[120:123]
	v_mfma_f32_16x16x32_bf16 v[108:111], v[136:139], v[202:205], v[108:111]
	v_mfma_f32_16x16x32_bf16 v[104:107], v[172:175], v[202:205], v[104:107]
	v_mfma_f32_16x16x32_bf16 v[92:95], v[136:139], v[210:213], v[92:95]
	v_mfma_f32_16x16x32_bf16 v[88:91], v[172:175], v[210:213], v[88:91]
	v_mfma_f32_16x16x32_bf16 v[76:79], v[136:139], v[218:221], v[76:79]
	v_mfma_f32_16x16x32_bf16 v[72:75], v[172:175], v[218:221], v[72:75]
	v_mfma_f32_16x16x32_bf16 v[124:127], v[168:171], v[198:201], v[124:127]
	v_mfma_f32_16x16x32_bf16 v[120:123], v[176:179], v[198:201], v[120:123]
	v_mfma_f32_16x16x32_bf16 v[108:111], v[168:171], v[206:209], v[108:111]
	v_mfma_f32_16x16x32_bf16 v[104:107], v[176:179], v[206:209], v[104:107]
	v_mfma_f32_16x16x32_bf16 v[92:95], v[168:171], v[214:217], v[92:95]
	v_mfma_f32_16x16x32_bf16 v[88:91], v[176:179], v[214:217], v[88:91]
	v_mfma_f32_16x16x32_bf16 v[76:79], v[168:171], v[222:225], v[76:79]
	v_mfma_f32_16x16x32_bf16 v[72:75], v[176:179], v[222:225], v[72:75]
	s_setprio 0
	s_barrier
	s_add_i32 s50, 0, 0x1c000
	s_add_i32 s28, s75, s53
	v_add_u32_e32 v164, s50, v143
	v_lshl_add_u64 v[140:141], v[140:141], 0, s[10:11]
	s_mov_b32 m0, s28
	ds_read_b128 v[226:229], v164
	ds_read_b128 v[230:233], v164 offset:1024
	ds_read_b128 v[234:237], v164 offset:2048
	ds_read_b128 v[238:241], v164 offset:3072
	global_load_lds_dwordx4 v[140:141], off
	v_lshl_add_u64 v[140:141], v[242:243], 0, s[10:11]
	s_add_i32 m0, s28, 0x2000
	s_nop 0
	global_load_lds_dwordx4 v[140:141], off
	s_barrier
	s_waitcnt lgkmcnt(0)
	s_setprio 1
	s_waitcnt lgkmcnt(0)
	v_mfma_f32_16x16x32_bf16 v[116:119], v[226:229], v[194:197], v[116:119]
	v_mfma_f32_16x16x32_bf16 v[112:115], v[234:237], v[194:197], v[112:115]
	v_mfma_f32_16x16x32_bf16 v[100:103], v[226:229], v[202:205], v[100:103]
	v_mfma_f32_16x16x32_bf16 v[96:99], v[234:237], v[202:205], v[96:99]
	v_mfma_f32_16x16x32_bf16 v[84:87], v[226:229], v[210:213], v[84:87]
	v_mfma_f32_16x16x32_bf16 v[80:83], v[234:237], v[210:213], v[80:83]
	v_mfma_f32_16x16x32_bf16 v[68:71], v[226:229], v[218:221], v[68:71]
	v_mfma_f32_16x16x32_bf16 v[64:67], v[234:237], v[218:221], v[64:67]
	v_mfma_f32_16x16x32_bf16 v[116:119], v[230:233], v[198:201], v[116:119]
	v_mfma_f32_16x16x32_bf16 v[112:115], v[238:241], v[198:201], v[112:115]
	v_mfma_f32_16x16x32_bf16 v[100:103], v[230:233], v[206:209], v[100:103]
	v_mfma_f32_16x16x32_bf16 v[96:99], v[238:241], v[206:209], v[96:99]
	v_mfma_f32_16x16x32_bf16 v[84:87], v[230:233], v[214:217], v[84:87]
	v_mfma_f32_16x16x32_bf16 v[80:83], v[238:241], v[214:217], v[80:83]
	v_mfma_f32_16x16x32_bf16 v[68:71], v[230:233], v[222:225], v[68:71]
	v_mfma_f32_16x16x32_bf16 v[64:67], v[238:241], v[222:225], v[64:67]
	s_setprio 0
	s_mov_b32 m0, s6
	v_lshl_add_u64 v[140:141], v[244:245], 0, s[10:11]
	s_barrier
	ds_read_b128 v[194:197], v153 offset:49152
	ds_read_b128 v[198:201], v153 offset:50176
	ds_read_b128 v[202:205], v153 offset:51200
	ds_read_b128 v[206:209], v153 offset:52224
	ds_read_b128 v[210:213], v153 offset:53248
	ds_read_b128 v[214:217], v153 offset:54272
	ds_read_b128 v[218:221], v153 offset:55296
	ds_read_b128 v[222:225], v153 offset:56320
	global_load_lds_dwordx4 v[140:141], off
	v_lshl_add_u64 v[140:141], v[246:247], 0, s[10:11]
	s_mov_b32 m0, s7
	s_nop 0
	global_load_lds_dwordx4 v[140:141], off
	s_barrier
	s_waitcnt lgkmcnt(0)
	s_setprio 1
	s_waitcnt lgkmcnt(0)
	v_mfma_f32_16x16x32_bf16 v[60:63], v[136:139], v[194:197], v[60:63]
	v_mfma_f32_16x16x32_bf16 v[56:59], v[172:175], v[194:197], v[56:59]
	v_mfma_f32_16x16x32_bf16 v[44:47], v[136:139], v[202:205], v[44:47]
	v_mfma_f32_16x16x32_bf16 v[40:43], v[172:175], v[202:205], v[40:43]
	v_mfma_f32_16x16x32_bf16 v[28:31], v[136:139], v[210:213], v[28:31]
	v_mfma_f32_16x16x32_bf16 v[24:27], v[172:175], v[210:213], v[24:27]
	v_mfma_f32_16x16x32_bf16 v[12:15], v[136:139], v[218:221], v[12:15]
	v_mfma_f32_16x16x32_bf16 v[8:11], v[172:175], v[218:221], v[8:11]
	v_mfma_f32_16x16x32_bf16 v[60:63], v[168:171], v[198:201], v[60:63]
	v_mfma_f32_16x16x32_bf16 v[56:59], v[176:179], v[198:201], v[56:59]
	v_mfma_f32_16x16x32_bf16 v[44:47], v[168:171], v[206:209], v[44:47]
	v_mfma_f32_16x16x32_bf16 v[40:43], v[176:179], v[206:209], v[40:43]
	v_mfma_f32_16x16x32_bf16 v[28:31], v[168:171], v[214:217], v[28:31]
	v_mfma_f32_16x16x32_bf16 v[24:27], v[176:179], v[214:217], v[24:27]
	v_mfma_f32_16x16x32_bf16 v[12:15], v[168:171], v[222:225], v[12:15]
	v_mfma_f32_16x16x32_bf16 v[8:11], v[176:179], v[222:225], v[8:11]
	s_setprio 0
	s_barrier
	s_add_u32 s28, s48, 0x40080
	s_addc_u32 s29, s49, 0
	s_add_i32 s48, s50, s53
	v_lshl_add_u64 v[136:137], s[28:29], 0, v[158:159]
	s_mov_b32 m0, s48
	s_nop 0
	global_load_lds_dwordx4 v[136:137], off
	v_lshl_add_u64 v[136:137], s[28:29], 0, v[162:163]
	s_add_i32 m0, s48, 0x2000
	s_nop 0
	global_load_lds_dwordx4 v[136:137], off
	s_waitcnt vmcnt(6)
	s_barrier
	s_setprio 1
	v_mfma_f32_16x16x32_bf16 v[52:55], v[226:229], v[194:197], v[52:55]
	v_mfma_f32_16x16x32_bf16 v[48:51], v[234:237], v[194:197], v[48:51]
	v_mfma_f32_16x16x32_bf16 v[36:39], v[226:229], v[202:205], v[36:39]
	v_mfma_f32_16x16x32_bf16 v[32:35], v[234:237], v[202:205], v[32:35]
	v_mfma_f32_16x16x32_bf16 v[20:23], v[226:229], v[210:213], v[20:23]
	v_mfma_f32_16x16x32_bf16 v[16:19], v[234:237], v[210:213], v[16:19]
	v_mfma_f32_16x16x32_bf16 v[4:7], v[226:229], v[218:221], v[4:7]
	v_mfma_f32_16x16x32_bf16 v[0:3], v[234:237], v[218:221], v[0:3]
	v_mfma_f32_16x16x32_bf16 v[52:55], v[230:233], v[198:201], v[52:55]
	v_mfma_f32_16x16x32_bf16 v[48:51], v[238:241], v[198:201], v[48:51]
	v_mfma_f32_16x16x32_bf16 v[36:39], v[230:233], v[206:209], v[36:39]
	v_mfma_f32_16x16x32_bf16 v[32:35], v[238:241], v[206:209], v[32:35]
	v_mfma_f32_16x16x32_bf16 v[20:23], v[230:233], v[214:217], v[20:23]
	v_mfma_f32_16x16x32_bf16 v[16:19], v[238:241], v[214:217], v[16:19]
	v_mfma_f32_16x16x32_bf16 v[4:7], v[230:233], v[222:225], v[4:7]
	v_mfma_f32_16x16x32_bf16 v[0:3], v[238:241], v[222:225], v[0:3]
	s_setprio 0
	s_add_i32 s74, s74, 2
	s_add_u32 s46, s46, 0x100
	s_addc_u32 s47, s47, 0
	s_add_u32 s72, s72, 0x100
	s_addc_u32 s73, s73, 0
	s_cmp_gt_u32 s74, 13
	s_barrier
	s_cbranch_scc0 .LBB0_898
	v_lshl_add_u32 v140, s44, 8, v142
	v_lshl_or_b32 v138, s26, 7, v145
	v_ashrrev_i32_e32 v141, 31, v140
	v_ashrrev_i32_e32 v139, 31, v138
	v_lshlrev_b64 v[136:137], 10, v[140:141]
	v_lshl_add_u64 v[136:137], v[136:137], 0, v[138:139]
	v_lshlrev_b64 v[136:137], 1, v[136:137]
	v_lshl_add_u64 v[168:169], s[38:39], 0, v[136:137]
	v_lshl_add_u64 v[172:173], s[40:41], 0, v[136:137]
	global_load_dwordx4 v[168:171], v[168:169], off
	v_mul_f32_e32 v124, 0xbfb8aa3b, v124
	global_load_dwordx4 v[172:175], v[172:173], off
	v_add_u32_e32 v202, 0x8000, v136
	global_load_dwordx4 v[198:201], v202, s[38:39]
	global_load_dwordx4 v[204:207], v202, s[40:41]
	v_add_u32_e32 v202, 0x10000, v136
	global_load_dwordx4 v[198:201], v202, s[38:39]
	global_load_dwordx4 v[204:207], v202, s[40:41]
	v_add_u32_e32 v202, 0x18000, v136
	global_load_dwordx4 v[198:201], v202, s[38:39]
	global_load_dwordx4 v[204:207], v202, s[40:41]
	v_add_u32_e32 v202, 0x40000, v136
	global_load_dwordx4 v[198:201], v202, s[38:39]
	global_load_dwordx4 v[204:207], v202, s[40:41]
	v_add_u32_e32 v202, 0x48000, v136
	global_load_dwordx4 v[198:201], v202, s[38:39]
	global_load_dwordx4 v[204:207], v202, s[40:41]
	v_add_u32_e32 v202, 0x50000, v136
	global_load_dwordx4 v[198:201], v202, s[38:39]
	global_load_dwordx4 v[204:207], v202, s[40:41]
	v_add_u32_e32 v202, 0x58000, v136
	global_load_dwordx4 v[198:201], v202, s[38:39]
	global_load_dwordx4 v[204:207], v202, s[40:41]
	v_mul_f32_e32 v116, 0xbfb8aa3b, v116
	v_mul_f32_e32 v112, 0xbfb8aa3b, v112
	v_mul_f32_e32 v125, 0xbfb8aa3b, v125
	v_mul_f32_e32 v117, 0xbfb8aa3b, v117
	v_mul_f32_e32 v113, 0xbfb8aa3b, v113
	v_mul_f32_e32 v120, 0xbfb8aa3b, v120
	v_mul_f32_e32 v121, 0xbfb8aa3b, v121
	v_mul_f32_e32 v118, 0xbfb8aa3b, v118
	v_mul_f32_e32 v114, 0xbfb8aa3b, v114
	v_mul_f32_e32 v119, 0xbfb8aa3b, v119
	v_exp_f32_e32 v124, v124
	v_exp_f32_e32 v116, v116
	v_exp_f32_e32 v112, v112
	v_exp_f32_e32 v125, v125
	v_exp_f32_e32 v117, v117
	v_exp_f32_e32 v113, v113
	v_exp_f32_e32 v120, v120
	v_exp_f32_e32 v121, v121
	v_exp_f32_e32 v118, v118
	v_exp_f32_e32 v114, v114
	v_exp_f32_e32 v119, v119
	v_mul_f32_e32 v126, 0xbfb8aa3b, v126
	v_mul_f32_e32 v122, 0xbfb8aa3b, v122
	v_mul_f32_e32 v123, 0xbfb8aa3b, v123
	v_mul_f32_e32 v115, 0xbfb8aa3b, v115
	v_exp_f32_e32 v126, v126
	v_exp_f32_e32 v122, v122
	v_exp_f32_e32 v141, v123
	v_exp_f32_e32 v164, v115
	v_add_f32_e32 v115, 1.0, v124
	v_add_f32_e32 v116, 1.0, v116
	v_add_f32_e32 v123, 1.0, v112
	v_add_f32_e32 v124, 1.0, v125
	v_add_f32_e32 v117, 1.0, v117
	v_add_f32_e32 v125, 1.0, v113
	v_mul_f32_e32 v127, 0xbfb8aa3b, v127
	v_add_f32_e32 v120, 1.0, v120
	v_add_f32_e32 v121, 1.0, v121
	v_add_f32_e32 v166, 1.0, v118
	v_add_f32_e32 v177, 1.0, v114
	v_add_f32_e32 v178, 1.0, v119
	v_rcp_f32_e32 v112, v115
	v_rcp_f32_e32 v114, v116
	v_rcp_f32_e32 v118, v123
	v_rcp_f32_e32 v115, v117
	v_rcp_f32_e32 v119, v125
	v_exp_f32_e32 v127, v127
	v_rcp_f32_e32 v116, v120
	v_rcp_f32_e32 v113, v124
	v_rcp_f32_e32 v117, v121
	v_add_f32_e32 v126, 1.0, v126
	v_add_f32_e32 v176, 1.0, v122
	v_rcp_f32_e32 v123, v178
	v_rcp_f32_e32 v120, v126
	v_rcp_f32_e32 v124, v176
	v_rcp_f32_e32 v126, v177
	v_add_f32_e32 v127, 1.0, v127
	v_rcp_f32_e32 v122, v166
	v_rcp_f32_e32 v121, v127
	v_mul_f32_e32 v108, 0xbfb8aa3b, v108
	v_mul_f32_e32 v100, 0xbfb8aa3b, v100
	v_mul_f32_e32 v96, 0xbfb8aa3b, v96
	v_mul_f32_e32 v109, 0xbfb8aa3b, v109
	v_mul_f32_e32 v101, 0xbfb8aa3b, v101
	v_mul_f32_e32 v97, 0xbfb8aa3b, v97
	v_mul_f32_e32 v104, 0xbfb8aa3b, v104
	v_mul_f32_e32 v105, 0xbfb8aa3b, v105
	v_exp_f32_e32 v108, v108
	v_exp_f32_e32 v100, v100
	v_exp_f32_e32 v96, v96
	v_exp_f32_e32 v109, v109
	v_exp_f32_e32 v101, v101
	v_exp_f32_e32 v97, v97
	v_exp_f32_e32 v104, v104
	v_exp_f32_e32 v105, v105
	v_mul_f32_e32 v110, 0xbfb8aa3b, v110
	v_mul_f32_e32 v102, 0xbfb8aa3b, v102
	s_waitcnt vmcnt(0)
	v_lshlrev_b32_e32 v176, 16, v168
	v_and_b32_e32 v177, 0xffff0000, v168
	v_lshlrev_b32_e32 v178, 16, v172
	v_and_b32_e32 v179, 0xffff0000, v172
	v_lshlrev_b32_e32 v196, 16, v174
	v_and_b32_e32 v197, 0xffff0000, v174
	v_lshlrev_b32_e32 v194, 16, v170
	v_and_b32_e32 v195, 0xffff0000, v170
	v_pk_mul_f32 v[114:115], v[114:115], v[178:179]
	v_pk_mul_f32 v[118:119], v[118:119], v[196:197]
	v_pk_fma_f32 v[112:113], v[112:113], v[176:177], v[114:115]
	v_pk_fma_f32 v[114:115], v[116:117], v[194:195], v[118:119]
	v_add_f32_e32 v118, 1.0, v141
	v_rcp_f32_e32 v125, v118
	v_add_f32_e32 v118, 1.0, v164
	v_rcp_f32_e32 v127, v118
	v_lshlrev_b32_e32 v172, 16, v173
	v_and_b32_e32 v173, 0xffff0000, v173
	v_lshlrev_b32_e32 v168, 16, v169
	v_and_b32_e32 v169, 0xffff0000, v169
	v_pk_mul_f32 v[122:123], v[122:123], v[172:173]
	v_lshlrev_b32_e32 v118, 16, v171
	v_pk_fma_f32 v[116:117], v[120:121], v[168:169], v[122:123]
	v_lshlrev_b32_e32 v120, 16, v175
	v_and_b32_e32 v121, 0xffff0000, v175
	v_and_b32_e32 v119, 0xffff0000, v171
	v_pk_mul_f32 v[120:121], v[126:127], v[120:121]
	v_cvt_pk_bf16_f32 v112, v112, v113
	v_pk_fma_f32 v[118:119], v[124:125], v[118:119], v[120:121]
	v_cvt_pk_bf16_f32 v113, v116, v117
	v_cvt_pk_bf16_f32 v114, v114, v115
	v_cvt_pk_bf16_f32 v115, v118, v119
	v_lshl_add_u64 v[116:117], s[58:59], 0, v[136:137]
	global_store_dwordx4 v[116:117], v[112:115], off
	v_exp_f32_e32 v110, v110
	v_exp_f32_e32 v102, v102
	v_or_b32_e32 v112, 16, v140
	v_ashrrev_i32_e32 v113, 31, v112
	v_lshlrev_b64 v[112:113], 10, v[112:113]
	v_lshl_add_u64 v[112:113], v[112:113], 0, v[138:139]
	v_lshlrev_b64 v[120:121], 1, v[112:113]
	v_lshl_add_u64 v[112:113], s[38:39], 0, v[120:121]
	v_lshl_add_u64 v[116:117], s[40:41], 0, v[120:121]
	global_load_dwordx4 v[112:115], v[112:113], off
	v_mul_f32_e32 v106, 0xbfb8aa3b, v106
	global_load_dwordx4 v[116:119], v[116:117], off
	v_add_f32_e32 v108, 1.0, v108
	v_add_f32_e32 v100, 1.0, v100
	v_add_f32_e32 v122, 1.0, v96
	v_add_f32_e32 v109, 1.0, v109
	v_add_f32_e32 v101, 1.0, v101
	v_add_f32_e32 v123, 1.0, v97
	v_mul_f32_e32 v98, 0xbfb8aa3b, v98
	v_exp_f32_e32 v106, v106
	v_add_f32_e32 v104, 1.0, v104
	v_add_f32_e32 v105, 1.0, v105
	v_rcp_f32_e32 v96, v108
	v_rcp_f32_e32 v100, v100
	v_rcp_f32_e32 v108, v122
	v_rcp_f32_e32 v97, v109
	v_rcp_f32_e32 v101, v101
	v_rcp_f32_e32 v109, v123
	v_exp_f32_e32 v98, v98
	v_rcp_f32_e32 v104, v104
	v_rcp_f32_e32 v105, v105
	v_add_f32_e32 v110, 1.0, v110
	v_add_f32_e32 v124, 1.0, v102
	v_rcp_f32_e32 v102, v110
	v_rcp_f32_e32 v110, v124
	v_mul_f32_e32 v111, 0xbfb8aa3b, v111
	v_add_f32_e32 v106, 1.0, v106
	v_mul_f32_e32 v103, 0xbfb8aa3b, v103
	v_add_f32_e32 v141, 1.0, v98
	v_rcp_f32_e32 v98, v106
	v_exp_f32_e32 v106, v103
	v_mul_f32_e32 v99, 0xbfb8aa3b, v99
	v_mul_f32_e32 v84, 0xbfb8aa3b, v84
	v_mul_f32_e32 v85, 0xbfb8aa3b, v85
	v_mul_f32_e32 v92, 0xbfb8aa3b, v92
	v_mul_f32_e32 v80, 0xbfb8aa3b, v80
	v_mul_f32_e32 v93, 0xbfb8aa3b, v93
	v_mul_f32_e32 v81, 0xbfb8aa3b, v81
	v_exp_f32_e32 v84, v84
	v_exp_f32_e32 v85, v85
	v_exp_f32_e32 v92, v92
	v_exp_f32_e32 v80, v80
	v_exp_f32_e32 v93, v93
	v_exp_f32_e32 v81, v81
	v_mul_f32_e32 v88, 0xbfb8aa3b, v88
	v_mul_f32_e32 v89, 0xbfb8aa3b, v89
	v_exp_f32_e32 v88, v88
	v_exp_f32_e32 v89, v89
	v_add_f32_e32 v84, 1.0, v84
	v_add_f32_e32 v85, 1.0, v85
	v_add_f32_e32 v92, 1.0, v92
	v_add_f32_e32 v93, 1.0, v93
	v_rcp_f32_e32 v84, v84
	v_rcp_f32_e32 v85, v85
	v_add_f32_e32 v88, 1.0, v88
	v_add_f32_e32 v89, 1.0, v89
	v_rcp_f32_e32 v88, v88
	v_rcp_f32_e32 v89, v89
	v_mul_f32_e32 v86, 0xbfb8aa3b, v86
	v_mul_f32_e32 v82, 0xbfb8aa3b, v82
	v_mul_f32_e32 v87, 0xbfb8aa3b, v87
	v_mul_f32_e32 v83, 0xbfb8aa3b, v83
	v_mul_f32_e32 v91, 0xbfb8aa3b, v91
	v_exp_f32_e32 v91, v91
	v_mul_f32_e32 v76, 0xbfb8aa3b, v76
	v_mul_f32_e32 v68, 0xbfb8aa3b, v68
	v_exp_f32_e32 v76, v76
	v_mul_f32_e32 v72, 0xbfb8aa3b, v72
	v_mul_f32_e32 v64, 0xbfb8aa3b, v64
	v_exp_f32_e32 v72, v72
	v_mul_f32_e32 v77, 0xbfb8aa3b, v77
	v_mul_f32_e32 v69, 0xbfb8aa3b, v69
	v_exp_f32_e32 v77, v77
	v_mul_f32_e32 v73, 0xbfb8aa3b, v73
	v_mul_f32_e32 v65, 0xbfb8aa3b, v65
	v_exp_f32_e32 v73, v73
	v_mul_f32_e32 v70, 0xbfb8aa3b, v70
	v_exp_f32_e32 v70, v70
	v_mul_f32_e32 v66, 0xbfb8aa3b, v66
	s_waitcnt vmcnt(0)
	v_lshlrev_b32_e32 v122, 16, v112
	v_and_b32_e32 v123, 0xffff0000, v112
	v_lshlrev_b32_e32 v124, 16, v116
	v_and_b32_e32 v125, 0xffff0000, v116
	v_lshlrev_b32_e32 v168, 16, v118
	v_and_b32_e32 v169, 0xffff0000, v118
	v_lshlrev_b32_e32 v126, 16, v114
	v_and_b32_e32 v127, 0xffff0000, v114
	v_pk_mul_f32 v[100:101], v[100:101], v[124:125]
	v_pk_mul_f32 v[108:109], v[108:109], v[168:169]
	v_pk_fma_f32 v[96:97], v[96:97], v[122:123], v[100:101]
	v_pk_fma_f32 v[100:101], v[104:105], v[126:127], v[108:109]
	v_exp_f32_e32 v105, v111
	v_rcp_f32_e32 v104, v141
	v_lshlrev_b32_e32 v108, 16, v113
	v_and_b32_e32 v109, 0xffff0000, v113
	v_add_f32_e32 v103, 1.0, v105
	v_add_f32_e32 v105, 1.0, v106
	v_rcp_f32_e32 v111, v105
	v_mul_f32_e32 v105, 0xbfb8aa3b, v107
	v_exp_f32_e32 v105, v105
	v_exp_f32_e32 v106, v99
	v_rcp_f32_e32 v103, v103
	v_lshlrev_b32_e32 v112, 16, v117
	v_add_f32_e32 v99, 1.0, v105
	v_add_f32_e32 v105, 1.0, v106
	v_rcp_f32_e32 v105, v105
	v_and_b32_e32 v113, 0xffff0000, v117
	v_rcp_f32_e32 v99, v99
	v_pk_mul_f32 v[110:111], v[110:111], v[112:113]
	v_lshlrev_b32_e32 v106, 16, v115
	v_pk_fma_f32 v[102:103], v[102:103], v[108:109], v[110:111]
	v_lshlrev_b32_e32 v108, 16, v119
	v_and_b32_e32 v109, 0xffff0000, v119
	v_and_b32_e32 v107, 0xffff0000, v115
	v_pk_mul_f32 v[104:105], v[104:105], v[108:109]
	v_cvt_pk_bf16_f32 v96, v96, v97
	v_pk_fma_f32 v[104:105], v[98:99], v[106:107], v[104:105]
	v_cvt_pk_bf16_f32 v97, v102, v103
	v_cvt_pk_bf16_f32 v98, v100, v101
	v_cvt_pk_bf16_f32 v99, v104, v105
	v_lshl_add_u64 v[100:101], s[58:59], 0, v[120:121]
	global_store_dwordx4 v[100:101], v[96:99], off
	v_add_f32_e32 v106, 1.0, v80
	v_add_f32_e32 v107, 1.0, v81
	v_or_b32_e32 v96, 32, v140
	v_ashrrev_i32_e32 v97, 31, v96
	v_lshlrev_b64 v[96:97], 10, v[96:97]
	v_lshl_add_u64 v[96:97], v[96:97], 0, v[138:139]
	v_lshlrev_b64 v[104:105], 1, v[96:97]
	v_lshl_add_u64 v[96:97], s[38:39], 0, v[104:105]
	v_lshl_add_u64 v[100:101], s[40:41], 0, v[104:105]
	global_load_dwordx4 v[96:99], v[96:97], off
	v_rcp_f32_e32 v80, v92
	global_load_dwordx4 v[100:103], v[100:101], off
	v_rcp_f32_e32 v92, v106
	v_rcp_f32_e32 v81, v93
	v_rcp_f32_e32 v93, v107
	v_mul_f32_e32 v71, 0xbfb8aa3b, v71
	v_exp_f32_e32 v71, v71
	v_mul_f32_e32 v78, 0xbfb8aa3b, v78
	v_exp_f32_e32 v78, v78
	v_mul_f32_e32 v75, 0xbfb8aa3b, v75
	v_add_f32_e32 v71, 1.0, v71
	v_rcp_f32_e32 v71, v71
	v_exp_f32_e32 v75, v75
	v_mul_f32_e32 v67, 0xbfb8aa3b, v67
	v_mul_f32_e32 v60, 0xbfb8aa3b, v60
	v_mul_f32_e32 v52, 0xbfb8aa3b, v52
	v_exp_f32_e32 v60, v60
	v_mul_f32_e32 v56, 0xbfb8aa3b, v56
	v_mul_f32_e32 v48, 0xbfb8aa3b, v48
	v_exp_f32_e32 v56, v56
	v_mul_f32_e32 v61, 0xbfb8aa3b, v61
	v_mul_f32_e32 v53, 0xbfb8aa3b, v53
	v_exp_f32_e32 v61, v61
	v_mul_f32_e32 v57, 0xbfb8aa3b, v57
	v_mul_f32_e32 v49, 0xbfb8aa3b, v49
	v_exp_f32_e32 v57, v57
	v_mul_f32_e32 v54, 0xbfb8aa3b, v54
	v_exp_f32_e32 v54, v54
	v_mul_f32_e32 v50, 0xbfb8aa3b, v50
	v_mul_f32_e32 v55, 0xbfb8aa3b, v55
	v_exp_f32_e32 v55, v55
	v_mul_f32_e32 v62, 0xbfb8aa3b, v62
	v_exp_f32_e32 v62, v62
	v_mul_f32_e32 v59, 0xbfb8aa3b, v59
	v_add_f32_e32 v55, 1.0, v55
	v_rcp_f32_e32 v55, v55
	v_exp_f32_e32 v59, v59
	v_mul_f32_e32 v51, 0xbfb8aa3b, v51
	v_mul_f32_e32 v44, 0xbfb8aa3b, v44
	v_mul_f32_e32 v36, 0xbfb8aa3b, v36
	v_exp_f32_e32 v44, v44
	v_mul_f32_e32 v40, 0xbfb8aa3b, v40
	v_mul_f32_e32 v32, 0xbfb8aa3b, v32
	v_exp_f32_e32 v40, v40
	v_mul_f32_e32 v45, 0xbfb8aa3b, v45
	v_mul_f32_e32 v37, 0xbfb8aa3b, v37
	v_exp_f32_e32 v45, v45
	v_mul_f32_e32 v41, 0xbfb8aa3b, v41
	v_mul_f32_e32 v33, 0xbfb8aa3b, v33
	v_exp_f32_e32 v41, v41
	v_mul_f32_e32 v38, 0xbfb8aa3b, v38
	v_exp_f32_e32 v38, v38
	v_mul_f32_e32 v34, 0xbfb8aa3b, v34
	v_mul_f32_e32 v39, 0xbfb8aa3b, v39
	v_exp_f32_e32 v39, v39
	v_mul_f32_e32 v46, 0xbfb8aa3b, v46
	v_exp_f32_e32 v46, v46
	v_mul_f32_e32 v43, 0xbfb8aa3b, v43
	v_add_f32_e32 v39, 1.0, v39
	v_rcp_f32_e32 v39, v39
	v_exp_f32_e32 v43, v43
	v_mul_f32_e32 v35, 0xbfb8aa3b, v35
	v_mul_f32_e32 v28, 0xbfb8aa3b, v28
	v_mul_f32_e32 v20, 0xbfb8aa3b, v20
	v_exp_f32_e32 v28, v28
	v_mul_f32_e32 v24, 0xbfb8aa3b, v24
	v_mul_f32_e32 v16, 0xbfb8aa3b, v16
	v_exp_f32_e32 v24, v24
	v_mul_f32_e32 v29, 0xbfb8aa3b, v29
	v_mul_f32_e32 v21, 0xbfb8aa3b, v21
	v_exp_f32_e32 v29, v29
	v_mul_f32_e32 v25, 0xbfb8aa3b, v25
	v_mul_f32_e32 v17, 0xbfb8aa3b, v17
	v_exp_f32_e32 v25, v25
	v_mul_f32_e32 v22, 0xbfb8aa3b, v22
	v_exp_f32_e32 v22, v22
	v_mul_f32_e32 v18, 0xbfb8aa3b, v18
	v_mul_f32_e32 v23, 0xbfb8aa3b, v23
	v_exp_f32_e32 v23, v23
	s_waitcnt vmcnt(0)
	v_lshlrev_b32_e32 v106, 16, v96
	v_and_b32_e32 v107, 0xffff0000, v96
	v_lshlrev_b32_e32 v108, 16, v100
	v_and_b32_e32 v109, 0xffff0000, v100
	v_lshlrev_b32_e32 v112, 16, v102
	v_and_b32_e32 v113, 0xffff0000, v102
	v_pk_mul_f32 v[84:85], v[84:85], v[108:109]
	v_lshlrev_b32_e32 v110, 16, v98
	v_pk_fma_f32 v[80:81], v[80:81], v[106:107], v[84:85]
	v_pk_mul_f32 v[84:85], v[92:93], v[112:113]
	v_exp_f32_e32 v93, v86
	v_and_b32_e32 v111, 0xffff0000, v98
	v_pk_fma_f32 v[84:85], v[88:89], v[110:111], v[84:85]
	v_mul_f32_e32 v89, 0xbfb8aa3b, v90
	v_mul_f32_e32 v92, 0xbfb8aa3b, v94
	v_exp_f32_e32 v89, v89
	v_exp_f32_e32 v90, v82
	v_exp_f32_e32 v92, v92
	v_add_f32_e32 v88, 1.0, v93
	v_exp_f32_e32 v93, v87
	v_add_f32_e32 v82, 1.0, v89
	v_add_f32_e32 v89, 1.0, v90
	v_mul_f32_e32 v90, 0xbfb8aa3b, v95
	v_add_f32_e32 v86, 1.0, v92
	v_exp_f32_e32 v92, v90
	v_rcp_f32_e32 v90, v89
	v_add_f32_e32 v89, 1.0, v93
	v_rcp_f32_e32 v88, v88
	v_rcp_f32_e32 v89, v89
	v_add_f32_e32 v87, 1.0, v92
	v_lshlrev_b32_e32 v94, 16, v101
	v_and_b32_e32 v95, 0xffff0000, v101
	v_rcp_f32_e32 v86, v86
	v_rcp_f32_e32 v87, v87
	v_pk_mul_f32 v[88:89], v[88:89], v[94:95]
	v_exp_f32_e32 v94, v83
	v_lshlrev_b32_e32 v92, 16, v97
	v_and_b32_e32 v93, 0xffff0000, v97
	v_pk_fma_f32 v[86:87], v[86:87], v[92:93], v[88:89]
	v_add_f32_e32 v88, 1.0, v94
	v_add_f32_e32 v83, 1.0, v91
	v_rcp_f32_e32 v91, v88
	v_rcp_f32_e32 v82, v82
	v_rcp_f32_e32 v83, v83
	v_lshlrev_b32_e32 v92, 16, v103
	v_and_b32_e32 v93, 0xffff0000, v103
	v_lshlrev_b32_e32 v88, 16, v99
	v_and_b32_e32 v89, 0xffff0000, v99
	v_pk_mul_f32 v[90:91], v[90:91], v[92:93]
	v_cvt_pk_bf16_f32 v80, v80, v81
	v_pk_fma_f32 v[88:89], v[82:83], v[88:89], v[90:91]
	v_cvt_pk_bf16_f32 v81, v86, v87
	v_cvt_pk_bf16_f32 v82, v84, v85
	v_cvt_pk_bf16_f32 v83, v88, v89
	v_lshl_add_u64 v[84:85], s[58:59], 0, v[104:105]
	global_store_dwordx4 v[84:85], v[80:83], off
	v_exp_f32_e32 v90, v68
	v_add_f32_e32 v68, 1.0, v76
	v_or_b32_e32 v80, 48, v140
	v_ashrrev_i32_e32 v81, 31, v80
	v_lshlrev_b64 v[80:81], 10, v[80:81]
	v_lshl_add_u64 v[80:81], v[80:81], 0, v[138:139]
	v_lshlrev_b64 v[88:89], 1, v[80:81]
	v_lshl_add_u64 v[80:81], s[38:39], 0, v[88:89]
	global_load_dwordx4 v[80:83], v[80:81], off
	v_lshl_add_u64 v[84:85], s[40:41], 0, v[88:89]
	global_load_dwordx4 v[84:87], v[84:85], off
	v_add_f32_e32 v76, 1.0, v90
	v_exp_f32_e32 v90, v64
	v_add_f32_e32 v64, 1.0, v72
	v_rcp_f32_e32 v76, v76
	v_rcp_f32_e32 v68, v68
	v_add_f32_e32 v72, 1.0, v90
	v_exp_f32_e32 v90, v69
	v_add_f32_e32 v69, 1.0, v77
	v_rcp_f32_e32 v69, v69
	v_rcp_f32_e32 v72, v72
	v_add_f32_e32 v77, 1.0, v90
	v_rcp_f32_e32 v77, v77
	v_rcp_f32_e32 v64, v64
	v_mul_f32_e32 v30, 0xbfb8aa3b, v30
	v_exp_f32_e32 v30, v30
	v_add_f32_e32 v23, 1.0, v23
	v_rcp_f32_e32 v23, v23
	v_mul_f32_e32 v27, 0xbfb8aa3b, v27
	v_exp_f32_e32 v27, v27
	v_mul_f32_e32 v19, 0xbfb8aa3b, v19
	v_mul_f32_e32 v12, 0xbfb8aa3b, v12
	v_mul_f32_e32 v4, 0xbfb8aa3b, v4
	v_exp_f32_e32 v12, v12
	v_mul_f32_e32 v8, 0xbfb8aa3b, v8
	v_mul_f32_e32 v0, 0xbfb8aa3b, v0
	v_exp_f32_e32 v8, v8
	v_mul_f32_e32 v13, 0xbfb8aa3b, v13
	v_mul_f32_e32 v5, 0xbfb8aa3b, v5
	v_exp_f32_e32 v13, v13
	v_mul_f32_e32 v9, 0xbfb8aa3b, v9
	v_mul_f32_e32 v1, 0xbfb8aa3b, v1
	v_exp_f32_e32 v9, v9
	v_mul_f32_e32 v6, 0xbfb8aa3b, v6
	v_exp_f32_e32 v6, v6
	v_mul_f32_e32 v2, 0xbfb8aa3b, v2
	v_mul_f32_e32 v7, 0xbfb8aa3b, v7
	v_exp_f32_e32 v7, v7
	v_mul_f32_e32 v14, 0xbfb8aa3b, v14
	v_exp_f32_e32 v14, v14
	v_mul_f32_e32 v11, 0xbfb8aa3b, v11
	v_add_f32_e32 v7, 1.0, v7
	v_rcp_f32_e32 v7, v7
	v_exp_f32_e32 v11, v11
	v_mul_f32_e32 v3, 0xbfb8aa3b, v3
	s_and_b64 vcc, exec, s[8:9]
	s_mov_b32 s26, s22
	s_mov_b32 s44, s20
	s_mov_b64 s[48:49], s[42:43]
	s_mov_b64 s[46:47], s[24:25]
	s_waitcnt vmcnt(0)
	v_lshlrev_b32_e32 v90, 16, v80
	v_and_b32_e32 v91, 0xffff0000, v80
	v_exp_f32_e32 v80, v65
	v_add_f32_e32 v65, 1.0, v73
	v_lshlrev_b32_e32 v92, 16, v84
	v_and_b32_e32 v93, 0xffff0000, v84
	v_add_f32_e32 v73, 1.0, v80
	v_rcp_f32_e32 v73, v73
	v_rcp_f32_e32 v65, v65
	v_pk_mul_f32 v[76:77], v[76:77], v[92:93]
	s_nop 0
	v_pk_fma_f32 v[68:69], v[68:69], v[90:91], v[76:77]
	v_lshlrev_b32_e32 v90, 16, v86
	v_and_b32_e32 v91, 0xffff0000, v86
	v_lshlrev_b32_e32 v76, 16, v82
	v_and_b32_e32 v77, 0xffff0000, v82
	v_pk_mul_f32 v[72:73], v[72:73], v[90:91]
	s_nop 0
	v_pk_fma_f32 v[72:73], v[64:65], v[76:77], v[72:73]
	v_add_f32_e32 v65, 1.0, v70
	v_mul_f32_e32 v70, 0xbfb8aa3b, v74
	v_exp_f32_e32 v74, v70
	v_exp_f32_e32 v76, v66
	v_rcp_f32_e32 v70, v65
	v_add_f32_e32 v64, 1.0, v78
	v_add_f32_e32 v65, 1.0, v74
	v_mul_f32_e32 v74, 0xbfb8aa3b, v79
	v_rcp_f32_e32 v66, v65
	v_add_f32_e32 v65, 1.0, v76
	v_exp_f32_e32 v76, v74
	v_rcp_f32_e32 v74, v65
	v_rcp_f32_e32 v64, v64
	v_lshlrev_b32_e32 v78, 16, v85
	v_add_f32_e32 v65, 1.0, v76
	v_rcp_f32_e32 v65, v65
	v_and_b32_e32 v79, 0xffff0000, v85
	v_pk_mul_f32 v[70:71], v[70:71], v[78:79]
	v_exp_f32_e32 v78, v67
	v_lshlrev_b32_e32 v76, 16, v81
	v_and_b32_e32 v77, 0xffff0000, v81
	v_pk_fma_f32 v[70:71], v[64:65], v[76:77], v[70:71]
	v_add_f32_e32 v64, 1.0, v75
	v_rcp_f32_e32 v67, v64
	v_add_f32_e32 v64, 1.0, v78
	v_rcp_f32_e32 v75, v64
	v_lshlrev_b32_e32 v76, 16, v87
	v_and_b32_e32 v77, 0xffff0000, v87
	v_lshlrev_b32_e32 v64, 16, v83
	v_and_b32_e32 v65, 0xffff0000, v83
	v_pk_mul_f32 v[74:75], v[74:75], v[76:77]
	s_nop 0
	v_pk_fma_f32 v[74:75], v[66:67], v[64:65], v[74:75]
	v_cvt_pk_bf16_f32 v64, v68, v69
	v_cvt_pk_bf16_f32 v65, v70, v71
	v_cvt_pk_bf16_f32 v66, v72, v73
	v_cvt_pk_bf16_f32 v67, v74, v75
	v_lshl_add_u64 v[68:69], s[58:59], 0, v[88:89]
	v_lshl_add_u64 v[72:73], v[136:137], 0, s[0:1]
	global_store_dwordx4 v[68:69], v[64:67], off
	v_lshl_add_u64 v[68:69], s[40:41], 0, v[72:73]
	global_load_dwordx4 v[68:71], v[68:69], off
	v_lshl_add_u64 v[64:65], s[38:39], 0, v[72:73]
	global_load_dwordx4 v[64:67], v[64:65], off
	v_exp_f32_e32 v74, v52
	v_add_f32_e32 v52, 1.0, v60
	v_rcp_f32_e32 v52, v52
	v_add_f32_e32 v60, 1.0, v74
	v_exp_f32_e32 v74, v48
	v_add_f32_e32 v48, 1.0, v56
	v_rcp_f32_e32 v60, v60
	v_rcp_f32_e32 v48, v48
	v_add_f32_e32 v56, 1.0, v74
	v_exp_f32_e32 v74, v53
	v_add_f32_e32 v53, 1.0, v61
	v_rcp_f32_e32 v53, v53
	v_rcp_f32_e32 v56, v56
	v_add_f32_e32 v61, 1.0, v74
	v_rcp_f32_e32 v61, v61
	s_waitcnt vmcnt(0)
	v_lshlrev_b32_e32 v76, 16, v68
	v_and_b32_e32 v77, 0xffff0000, v68
	v_lshlrev_b32_e32 v74, 16, v64
	v_and_b32_e32 v75, 0xffff0000, v64
	v_exp_f32_e32 v64, v49
	v_add_f32_e32 v49, 1.0, v57
	v_rcp_f32_e32 v49, v49
	v_pk_mul_f32 v[60:61], v[60:61], v[76:77]
	v_add_f32_e32 v57, 1.0, v64
	v_rcp_f32_e32 v57, v57
	v_pk_fma_f32 v[52:53], v[52:53], v[74:75], v[60:61]
	v_lshlrev_b32_e32 v74, 16, v70
	v_and_b32_e32 v75, 0xffff0000, v70
	v_lshlrev_b32_e32 v60, 16, v66
	v_and_b32_e32 v61, 0xffff0000, v66
	v_pk_mul_f32 v[56:57], v[56:57], v[74:75]
	s_nop 0
	v_pk_fma_f32 v[56:57], v[48:49], v[60:61], v[56:57]
	v_add_f32_e32 v49, 1.0, v54
	v_mul_f32_e32 v54, 0xbfb8aa3b, v58
	v_exp_f32_e32 v58, v54
	v_exp_f32_e32 v60, v50
	v_rcp_f32_e32 v54, v49
	v_add_f32_e32 v48, 1.0, v62
	v_add_f32_e32 v49, 1.0, v58
	v_mul_f32_e32 v58, 0xbfb8aa3b, v63
	v_rcp_f32_e32 v50, v49
	v_add_f32_e32 v49, 1.0, v60
	v_exp_f32_e32 v60, v58
	v_rcp_f32_e32 v58, v49
	v_rcp_f32_e32 v48, v48
	v_lshlrev_b32_e32 v62, 16, v69
	v_add_f32_e32 v49, 1.0, v60
	v_rcp_f32_e32 v49, v49
	v_and_b32_e32 v63, 0xffff0000, v69
	v_pk_mul_f32 v[54:55], v[54:55], v[62:63]
	v_exp_f32_e32 v62, v51
	v_lshlrev_b32_e32 v60, 16, v65
	v_and_b32_e32 v61, 0xffff0000, v65
	v_pk_fma_f32 v[54:55], v[48:49], v[60:61], v[54:55]
	v_add_f32_e32 v48, 1.0, v59
	v_rcp_f32_e32 v51, v48
	v_add_f32_e32 v48, 1.0, v62
	v_rcp_f32_e32 v59, v48
	v_lshlrev_b32_e32 v60, 16, v71
	v_and_b32_e32 v61, 0xffff0000, v71
	v_lshlrev_b32_e32 v48, 16, v67
	v_and_b32_e32 v49, 0xffff0000, v67
	v_pk_mul_f32 v[58:59], v[58:59], v[60:61]
	s_nop 0
	v_pk_fma_f32 v[58:59], v[50:51], v[48:49], v[58:59]
	v_cvt_pk_bf16_f32 v48, v52, v53
	v_cvt_pk_bf16_f32 v49, v54, v55
	v_cvt_pk_bf16_f32 v50, v56, v57
	v_cvt_pk_bf16_f32 v51, v58, v59
	v_lshl_add_u64 v[52:53], s[58:59], 0, v[72:73]
	v_lshl_add_u64 v[56:57], v[136:137], 0, s[12:13]
	global_store_dwordx4 v[52:53], v[48:51], off
	v_lshl_add_u64 v[52:53], s[40:41], 0, v[56:57]
	global_load_dwordx4 v[52:55], v[52:53], off
	v_lshl_add_u64 v[48:49], s[38:39], 0, v[56:57]
	global_load_dwordx4 v[48:51], v[48:49], off
	v_exp_f32_e32 v58, v36
	v_add_f32_e32 v36, 1.0, v44
	v_rcp_f32_e32 v36, v36
	v_add_f32_e32 v44, 1.0, v58
	v_exp_f32_e32 v58, v32
	v_add_f32_e32 v32, 1.0, v40
	v_rcp_f32_e32 v44, v44
	v_rcp_f32_e32 v32, v32
	v_add_f32_e32 v40, 1.0, v58
	v_exp_f32_e32 v58, v37
	v_add_f32_e32 v37, 1.0, v45
	v_rcp_f32_e32 v37, v37
	v_rcp_f32_e32 v40, v40
	v_add_f32_e32 v45, 1.0, v58
	v_rcp_f32_e32 v45, v45
	s_waitcnt vmcnt(0)
	v_lshlrev_b32_e32 v60, 16, v52
	v_and_b32_e32 v61, 0xffff0000, v52
	v_lshlrev_b32_e32 v58, 16, v48
	v_and_b32_e32 v59, 0xffff0000, v48
	v_exp_f32_e32 v48, v33
	v_add_f32_e32 v33, 1.0, v41
	v_rcp_f32_e32 v33, v33
	v_pk_mul_f32 v[44:45], v[44:45], v[60:61]
	v_add_f32_e32 v41, 1.0, v48
	v_rcp_f32_e32 v41, v41
	v_pk_fma_f32 v[36:37], v[36:37], v[58:59], v[44:45]
	v_lshlrev_b32_e32 v58, 16, v54
	v_and_b32_e32 v59, 0xffff0000, v54
	v_lshlrev_b32_e32 v44, 16, v50
	v_and_b32_e32 v45, 0xffff0000, v50
	v_pk_mul_f32 v[40:41], v[40:41], v[58:59]
	s_nop 0
	v_pk_fma_f32 v[40:41], v[32:33], v[44:45], v[40:41]
	v_add_f32_e32 v33, 1.0, v38
	v_mul_f32_e32 v38, 0xbfb8aa3b, v42
	v_exp_f32_e32 v42, v38
	v_exp_f32_e32 v44, v34
	v_rcp_f32_e32 v38, v33
	v_add_f32_e32 v32, 1.0, v46
	v_add_f32_e32 v33, 1.0, v42
	v_mul_f32_e32 v42, 0xbfb8aa3b, v47
	v_rcp_f32_e32 v34, v33
	v_add_f32_e32 v33, 1.0, v44
	v_exp_f32_e32 v44, v42
	v_rcp_f32_e32 v42, v33
	v_rcp_f32_e32 v32, v32
	v_lshlrev_b32_e32 v46, 16, v53
	v_add_f32_e32 v33, 1.0, v44
	v_rcp_f32_e32 v33, v33
	v_and_b32_e32 v47, 0xffff0000, v53
	v_pk_mul_f32 v[38:39], v[38:39], v[46:47]
	v_exp_f32_e32 v46, v35
	v_lshlrev_b32_e32 v44, 16, v49
	v_and_b32_e32 v45, 0xffff0000, v49
	v_pk_fma_f32 v[38:39], v[32:33], v[44:45], v[38:39]
	v_add_f32_e32 v32, 1.0, v43
	v_rcp_f32_e32 v35, v32
	v_add_f32_e32 v32, 1.0, v46
	v_rcp_f32_e32 v43, v32
	v_lshlrev_b32_e32 v44, 16, v55
	v_and_b32_e32 v45, 0xffff0000, v55
	v_lshlrev_b32_e32 v32, 16, v51
	v_and_b32_e32 v33, 0xffff0000, v51
	v_pk_mul_f32 v[42:43], v[42:43], v[44:45]
	s_nop 0
	v_pk_fma_f32 v[42:43], v[34:35], v[32:33], v[42:43]
	v_cvt_pk_bf16_f32 v32, v36, v37
	v_cvt_pk_bf16_f32 v33, v38, v39
	v_cvt_pk_bf16_f32 v34, v40, v41
	v_cvt_pk_bf16_f32 v35, v42, v43
	v_lshl_add_u64 v[36:37], s[58:59], 0, v[56:57]
	v_lshl_add_u64 v[40:41], v[136:137], 0, s[14:15]
	global_store_dwordx4 v[36:37], v[32:35], off
	v_lshl_add_u64 v[36:37], s[40:41], 0, v[40:41]
	global_load_dwordx4 v[36:39], v[36:37], off
	v_lshl_add_u64 v[32:33], s[38:39], 0, v[40:41]
	global_load_dwordx4 v[32:35], v[32:33], off
	v_exp_f32_e32 v42, v20
	v_add_f32_e32 v20, 1.0, v28
	v_rcp_f32_e32 v20, v20
	v_add_f32_e32 v28, 1.0, v42
	v_exp_f32_e32 v42, v16
	v_add_f32_e32 v16, 1.0, v24
	v_rcp_f32_e32 v28, v28
	v_rcp_f32_e32 v16, v16
	v_add_f32_e32 v24, 1.0, v42
	v_exp_f32_e32 v42, v21
	v_add_f32_e32 v21, 1.0, v29
	v_rcp_f32_e32 v21, v21
	v_rcp_f32_e32 v24, v24
	v_add_f32_e32 v29, 1.0, v42
	v_rcp_f32_e32 v29, v29
	s_waitcnt vmcnt(0)
	v_lshlrev_b32_e32 v44, 16, v36
	v_and_b32_e32 v45, 0xffff0000, v36
	v_lshlrev_b32_e32 v42, 16, v32
	v_and_b32_e32 v43, 0xffff0000, v32
	v_exp_f32_e32 v32, v17
	v_add_f32_e32 v17, 1.0, v25
	v_rcp_f32_e32 v17, v17
	v_pk_mul_f32 v[28:29], v[28:29], v[44:45]
	v_add_f32_e32 v25, 1.0, v32
	v_rcp_f32_e32 v25, v25
	v_pk_fma_f32 v[20:21], v[20:21], v[42:43], v[28:29]
	v_lshlrev_b32_e32 v42, 16, v38
	v_and_b32_e32 v43, 0xffff0000, v38
	v_lshlrev_b32_e32 v28, 16, v34
	v_and_b32_e32 v29, 0xffff0000, v34
	v_pk_mul_f32 v[24:25], v[24:25], v[42:43]
	s_nop 0
	v_pk_fma_f32 v[24:25], v[16:17], v[28:29], v[24:25]
	v_add_f32_e32 v17, 1.0, v22
	v_mul_f32_e32 v22, 0xbfb8aa3b, v26
	v_exp_f32_e32 v26, v22
	v_exp_f32_e32 v28, v18
	v_rcp_f32_e32 v22, v17
	v_add_f32_e32 v16, 1.0, v30
	v_add_f32_e32 v17, 1.0, v26
	v_mul_f32_e32 v26, 0xbfb8aa3b, v31
	v_rcp_f32_e32 v18, v17
	v_add_f32_e32 v17, 1.0, v28
	v_exp_f32_e32 v28, v26
	v_rcp_f32_e32 v26, v17
	v_rcp_f32_e32 v16, v16
	v_lshlrev_b32_e32 v30, 16, v37
	v_add_f32_e32 v17, 1.0, v28
	v_rcp_f32_e32 v17, v17
	v_and_b32_e32 v31, 0xffff0000, v37
	v_pk_mul_f32 v[22:23], v[22:23], v[30:31]
	v_exp_f32_e32 v30, v19
	v_lshlrev_b32_e32 v28, 16, v33
	v_and_b32_e32 v29, 0xffff0000, v33
	v_pk_fma_f32 v[22:23], v[16:17], v[28:29], v[22:23]
	v_add_f32_e32 v16, 1.0, v27
	v_rcp_f32_e32 v19, v16
	v_add_f32_e32 v16, 1.0, v30
	v_rcp_f32_e32 v27, v16
	v_lshlrev_b32_e32 v28, 16, v39
	v_and_b32_e32 v29, 0xffff0000, v39
	v_lshlrev_b32_e32 v16, 16, v35
	v_and_b32_e32 v17, 0xffff0000, v35
	v_pk_mul_f32 v[26:27], v[26:27], v[28:29]
	s_nop 0
	v_pk_fma_f32 v[26:27], v[18:19], v[16:17], v[26:27]
	v_cvt_pk_bf16_f32 v16, v20, v21
	v_cvt_pk_bf16_f32 v17, v22, v23
	v_cvt_pk_bf16_f32 v18, v24, v25
	v_cvt_pk_bf16_f32 v19, v26, v27
	v_lshl_add_u64 v[20:21], s[58:59], 0, v[40:41]
	v_lshl_add_u64 v[24:25], v[136:137], 0, s[16:17]
	global_store_dwordx4 v[20:21], v[16:19], off
	v_lshl_add_u64 v[20:21], s[40:41], 0, v[24:25]
	global_load_dwordx4 v[20:23], v[20:21], off
	v_lshl_add_u64 v[16:17], s[38:39], 0, v[24:25]
	global_load_dwordx4 v[16:19], v[16:17], off
	v_exp_f32_e32 v26, v4
	v_add_f32_e32 v4, 1.0, v12
	v_rcp_f32_e32 v4, v4
	v_add_f32_e32 v12, 1.0, v26
	v_exp_f32_e32 v26, v0
	v_add_f32_e32 v0, 1.0, v8
	v_rcp_f32_e32 v12, v12
	v_rcp_f32_e32 v0, v0
	v_add_f32_e32 v8, 1.0, v26
	v_exp_f32_e32 v26, v5
	v_add_f32_e32 v5, 1.0, v13
	v_rcp_f32_e32 v5, v5
	v_rcp_f32_e32 v8, v8
	v_add_f32_e32 v13, 1.0, v26
	v_rcp_f32_e32 v13, v13
	s_waitcnt vmcnt(0)
	v_lshlrev_b32_e32 v28, 16, v20
	v_and_b32_e32 v29, 0xffff0000, v20
	v_lshlrev_b32_e32 v26, 16, v16
	v_and_b32_e32 v27, 0xffff0000, v16
	v_exp_f32_e32 v16, v1
	v_add_f32_e32 v1, 1.0, v9
	v_rcp_f32_e32 v1, v1
	v_pk_mul_f32 v[12:13], v[12:13], v[28:29]
	v_add_f32_e32 v9, 1.0, v16
	v_rcp_f32_e32 v9, v9
	v_pk_fma_f32 v[4:5], v[4:5], v[26:27], v[12:13]
	v_lshlrev_b32_e32 v26, 16, v22
	v_and_b32_e32 v27, 0xffff0000, v22
	v_lshlrev_b32_e32 v12, 16, v18
	v_and_b32_e32 v13, 0xffff0000, v18
	v_pk_mul_f32 v[8:9], v[8:9], v[26:27]
	s_nop 0
	v_pk_fma_f32 v[8:9], v[0:1], v[12:13], v[8:9]
	v_add_f32_e32 v1, 1.0, v6
	v_mul_f32_e32 v6, 0xbfb8aa3b, v10
	v_exp_f32_e32 v10, v6
	v_exp_f32_e32 v12, v2
	v_rcp_f32_e32 v6, v1
	v_add_f32_e32 v0, 1.0, v14
	v_add_f32_e32 v1, 1.0, v10
	v_mul_f32_e32 v10, 0xbfb8aa3b, v15
	v_rcp_f32_e32 v2, v1
	v_add_f32_e32 v1, 1.0, v12
	v_exp_f32_e32 v12, v10
	v_rcp_f32_e32 v10, v1
	v_rcp_f32_e32 v0, v0
	v_lshlrev_b32_e32 v14, 16, v21
	v_add_f32_e32 v1, 1.0, v12
	v_rcp_f32_e32 v1, v1
	v_and_b32_e32 v15, 0xffff0000, v21
	v_pk_mul_f32 v[6:7], v[6:7], v[14:15]
	v_exp_f32_e32 v14, v3
	v_lshlrev_b32_e32 v12, 16, v17
	v_and_b32_e32 v13, 0xffff0000, v17
	v_pk_fma_f32 v[6:7], v[0:1], v[12:13], v[6:7]
	v_add_f32_e32 v0, 1.0, v11
	v_rcp_f32_e32 v3, v0
	v_add_f32_e32 v0, 1.0, v14
	v_rcp_f32_e32 v11, v0
	v_lshlrev_b32_e32 v12, 16, v23
	v_and_b32_e32 v13, 0xffff0000, v23
	v_lshlrev_b32_e32 v0, 16, v19
	v_and_b32_e32 v1, 0xffff0000, v19
	v_pk_mul_f32 v[10:11], v[10:11], v[12:13]
	s_nop 0
	v_pk_fma_f32 v[10:11], v[2:3], v[0:1], v[10:11]
	v_cvt_pk_bf16_f32 v0, v4, v5
	v_cvt_pk_bf16_f32 v1, v6, v7
	v_cvt_pk_bf16_f32 v2, v8, v9
	v_cvt_pk_bf16_f32 v3, v10, v11
	v_lshl_add_u64 v[4:5], s[58:59], 0, v[24:25]
	global_store_dwordx4 v[4:5], v[0:3], off
	s_cbranch_vccz .LBB0_895
	s_waitcnt vmcnt(0)
	s_cmpk_gt_u32 s3, 0xff
	s_cbranch_scc1 .LBB0_902
	s_barrier
